# FFT phase: all 16 row loads of a thread in flight before the LDS writes
# baseline (speedup 1.0000x reference)
; #define GAS __attribute__((address_space(1)))
; #define LAS __attribute__((address_space(3)))
; __device__ __forceinline__ void fft_phase(Frame& F, const bf16* Yc, bf16* Y) {
;     ...
;     for (int item = F.vcu; item < 256; item += F.G) {
;         const int b = item >> 7, g = (item >> 4) & 7, q4 = item & 15;
;         const bf16* src = Yc + ((size_t)(b * 128 + g * 16 + q4) * SEQ + t) * 8;
;         LAS unsigned char* lt = buf + 16 * (t + (t >> 5));
; #pragma unroll 1
;         for (int i = 0; i < 16; i += 8) { v4u v[8];
; #pragma unroll
;             for (int j = 0; j < 8; ++j) v[j] = *(const GAS v4u*)(src + (size_t)(512 * (i + j)) * 8);
; #pragma unroll
;             for (int j = 0; j < 8; ++j) *(LAS v4u*)(lt + 8464 * (i + j)) = v[j]; }
;         __syncthreads();
.LBB0_195:
	global_load_dwordx4 v[4:7], v[2:3], off
	s_mov_b32 s12, 0x2000
	s_mov_b32 s13, 0
	v_lshl_add_u64 v[8:9], v[2:3], 0, s[12:13]
	global_load_dwordx4 v[138:141], v[8:9], off
	s_mov_b32 s12, 0x4000
	s_mov_b32 s13, 0
	v_lshl_add_u64 v[8:9], v[2:3], 0, s[12:13]
	global_load_dwordx4 v[142:145], v[8:9], off
	s_mov_b32 s12, 0x6000
	s_mov_b32 s13, 0
	v_lshl_add_u64 v[8:9], v[2:3], 0, s[12:13]
	global_load_dwordx4 v[146:149], v[8:9], off
	s_mov_b32 s12, 0x8000
	s_mov_b32 s13, 0
	v_lshl_add_u64 v[8:9], v[2:3], 0, s[12:13]
	global_load_dwordx4 v[150:153], v[8:9], off
	s_mov_b32 s12, 0xa000
	s_mov_b32 s13, 0
	v_lshl_add_u64 v[8:9], v[2:3], 0, s[12:13]
	global_load_dwordx4 v[154:157], v[8:9], off
	s_mov_b32 s12, 0xc000
	s_mov_b32 s13, 0
	v_lshl_add_u64 v[8:9], v[2:3], 0, s[12:13]
	global_load_dwordx4 v[158:161], v[8:9], off
	s_mov_b32 s12, 0xe000
	s_mov_b32 s13, 0
	v_lshl_add_u64 v[8:9], v[2:3], 0, s[12:13]
	global_load_dwordx4 v[162:165], v[8:9], off
	s_mov_b32 s12, 0x10000
	s_mov_b32 s13, 0
	v_lshl_add_u64 v[8:9], v[2:3], 0, s[12:13]
	global_load_dwordx4 v[200:203], v[8:9], off
	s_mov_b32 s12, 0x12000
	s_mov_b32 s13, 0
	v_lshl_add_u64 v[8:9], v[2:3], 0, s[12:13]
	global_load_dwordx4 v[204:207], v[8:9], off
	s_mov_b32 s12, 0x14000
	s_mov_b32 s13, 0
	v_lshl_add_u64 v[8:9], v[2:3], 0, s[12:13]
	global_load_dwordx4 v[208:211], v[8:9], off
	s_mov_b32 s12, 0x16000
	s_mov_b32 s13, 0
	v_lshl_add_u64 v[8:9], v[2:3], 0, s[12:13]
	global_load_dwordx4 v[212:215], v[8:9], off
	s_mov_b32 s12, 0x18000
	s_mov_b32 s13, 0
	v_lshl_add_u64 v[8:9], v[2:3], 0, s[12:13]
	global_load_dwordx4 v[216:219], v[8:9], off
	s_mov_b32 s12, 0x1a000
	s_mov_b32 s13, 0
	v_lshl_add_u64 v[8:9], v[2:3], 0, s[12:13]
	global_load_dwordx4 v[220:223], v[8:9], off
	s_mov_b32 s12, 0x1c000
	s_mov_b32 s13, 0
	v_lshl_add_u64 v[8:9], v[2:3], 0, s[12:13]
	global_load_dwordx4 v[224:227], v[8:9], off
	s_mov_b32 s12, 0x1e000
	s_mov_b32 s13, 0
	v_lshl_add_u64 v[8:9], v[2:3], 0, s[12:13]
	global_load_dwordx4 v[228:231], v[8:9], off
	v_add_u32_e32 v8, 0x10880, v166
	s_waitcnt vmcnt(15)
	ds_write_b128 v166, v[4:7]
	s_waitcnt vmcnt(14)
	ds_write_b128 v166, v[138:141] offset:8464
	s_waitcnt vmcnt(13)
	ds_write_b128 v166, v[142:145] offset:16928
	s_waitcnt vmcnt(12)
	ds_write_b128 v166, v[146:149] offset:25392
	s_waitcnt vmcnt(11)
	ds_write_b128 v166, v[150:153] offset:33856
	s_waitcnt vmcnt(10)
	ds_write_b128 v166, v[154:157] offset:42320
	s_waitcnt vmcnt(9)
	ds_write_b128 v166, v[158:161] offset:50784
	s_waitcnt vmcnt(8)
	ds_write_b128 v166, v[162:165] offset:59248
	s_waitcnt vmcnt(7)
	ds_write_b128 v8, v[200:203]
	s_waitcnt vmcnt(6)
	ds_write_b128 v8, v[204:207] offset:8464
	s_waitcnt vmcnt(5)
	ds_write_b128 v8, v[208:211] offset:16928
	s_waitcnt vmcnt(4)
	ds_write_b128 v8, v[212:215] offset:25392
	s_waitcnt vmcnt(3)
	ds_write_b128 v8, v[216:219] offset:33856
	s_waitcnt vmcnt(2)
	ds_write_b128 v8, v[220:223] offset:42320
	s_waitcnt vmcnt(1)
	ds_write_b128 v8, v[224:227] offset:50784
	s_waitcnt vmcnt(0)
	ds_write_b128 v8, v[228:231] offset:59248
	s_mov_b32 s2, 8
	s_mov_b32 s0, 0
	s_mov_b64 s[4:5], -1
	s_waitcnt lgkmcnt(0)
	s_barrier
